# plus residual GEMM: next unit's residual-tile loads hoisted above the epilogue into dead fragment registers, counted vmcnt
# speedup vs baseline: 1.0037x; 1.0037x over previous
; __device__ __forceinline__ float bf_lo(unsigned w) { return __uint_as_float(w << 16); }
; __device__ __forceinline__ float bf_hi(unsigned w) { return __uint_as_float(w & 0xffff0000u); }
;     __device__ __forceinline__ void init(f32x4 (&acc)[2][2][4][2], const pg8::Unit&, int, int, int, int) const { acc_zero(acc); }
;     __device__ __forceinline__ void init(f32x4 (&acc)[2][2][4][2], const pg8::Unit&, int, int, int, int) const { acc_zero(acc); }
;     __device__ __forceinline__ void init(f32x4 (&acc)[2][2][4][2], const pg8::Unit&, int, int, int, int) const { acc_zero(acc); }
;     __device__ __forceinline__ void init(f32x4 (&acc)[2][2][4][2], const pg8::Unit&, int, int, int, int) const { acc_zero(acc); }
;     __device__ __forceinline__ void init(f32x4 (&acc)[2][2][4][2], const pg8::Unit& u, int wr, int wc, int fr, int fq) const {
;         const int col0 = u.pn * 256 + wc * 32 + 8 * fq;
;         const size_t off0 = (size_t)(u.pm * 256 + wr * 64 + fr) * D + col0;
; #pragma unroll
;         for (int ai = 0; ai < 2; ++ai)
; #pragma unroll
;             for (int m = 0; m < 4; ++m)
; #pragma unroll
;                 for (int bj = 0; bj < 2; ++bj) {
;                     const size_t off = off0 + (size_t)(ai * 128 + m * 16) * D + bj * 128;
;                     if (BASE_F32) { acc[ai][bj][m][0] = *(const f32x4*)(base32 + off); acc[ai][bj][m][1] = *(const f32x4*)(base32 + off + 4); }
;                     else { const u32x4 w = *(const u32x4*)(xb + off);
;                         acc[ai][bj][m][0] = (f32x4){bf_lo(w.x), bf_hi(w.x), bf_lo(w.y), bf_hi(w.y)}; acc[ai][bj][m][1] = (f32x4){bf_lo(w.z), bf_hi(w.z), bf_lo(w.w), bf_hi(w.w)}; }
;                 }
.LBB0_585:
	s_waitcnt vmcnt(16)
	v_lshlrev_b32_e32 v114, 16, v156
	v_and_b32_e32 v115, 0xffff0000, v156
	v_lshlrev_b32_e32 v116, 16, v157
	v_and_b32_e32 v117, 0xffff0000, v157
	v_lshlrev_b32_e32 v118, 16, v158
	v_and_b32_e32 v119, 0xffff0000, v158
	v_lshlrev_b32_e32 v120, 16, v159
	v_and_b32_e32 v121, 0xffff0000, v159
	v_lshlrev_b32_e32 v122, 16, v160
	v_and_b32_e32 v123, 0xffff0000, v160
	v_lshlrev_b32_e32 v124, 16, v161
	v_and_b32_e32 v125, 0xffff0000, v161
	v_lshlrev_b32_e32 v126, 16, v162
	v_and_b32_e32 v127, 0xffff0000, v162
	v_lshlrev_b32_e32 v128, 16, v163
	v_and_b32_e32 v129, 0xffff0000, v163
	v_lshlrev_b32_e32 v94, 16, v164
	v_and_b32_e32 v95, 0xffff0000, v164
	v_lshlrev_b32_e32 v96, 16, v165
	v_and_b32_e32 v97, 0xffff0000, v165
	v_lshlrev_b32_e32 v98, 16, v166
	v_and_b32_e32 v99, 0xffff0000, v166
	v_lshlrev_b32_e32 v100, 16, v167
	v_and_b32_e32 v101, 0xffff0000, v167
	v_lshlrev_b32_e32 v102, 16, v168
	v_and_b32_e32 v103, 0xffff0000, v168
	v_lshlrev_b32_e32 v104, 16, v169
	v_and_b32_e32 v105, 0xffff0000, v169
	v_lshlrev_b32_e32 v106, 16, v170
	v_and_b32_e32 v107, 0xffff0000, v170
	v_lshlrev_b32_e32 v108, 16, v171
	v_and_b32_e32 v109, 0xffff0000, v171
	v_lshlrev_b32_e32 v62, 16, v190
	v_and_b32_e32 v63, 0xffff0000, v190
	v_lshlrev_b32_e32 v64, 16, v191
	v_and_b32_e32 v65, 0xffff0000, v191
	v_lshlrev_b32_e32 v66, 16, v192
	v_and_b32_e32 v67, 0xffff0000, v192
	v_lshlrev_b32_e32 v68, 16, v193
	v_and_b32_e32 v69, 0xffff0000, v193
	v_lshlrev_b32_e32 v70, 16, v194
	v_and_b32_e32 v71, 0xffff0000, v194
	v_lshlrev_b32_e32 v72, 16, v195
	v_and_b32_e32 v73, 0xffff0000, v195
	v_lshlrev_b32_e32 v78, 16, v196
	v_and_b32_e32 v79, 0xffff0000, v196
	v_lshlrev_b32_e32 v80, 16, v197
	v_and_b32_e32 v81, 0xffff0000, v197
	v_lshlrev_b32_e32 v22, 16, v198
	v_and_b32_e32 v23, 0xffff0000, v198
	v_lshlrev_b32_e32 v24, 16, v199
	v_and_b32_e32 v25, 0xffff0000, v199
	v_lshlrev_b32_e32 v34, 16, v200
	v_and_b32_e32 v35, 0xffff0000, v200
	v_lshlrev_b32_e32 v36, 16, v201
	v_and_b32_e32 v37, 0xffff0000, v201
	v_lshlrev_b32_e32 v38, 16, v202
	v_and_b32_e32 v39, 0xffff0000, v202
	v_lshlrev_b32_e32 v40, 16, v203
	v_and_b32_e32 v41, 0xffff0000, v203
	v_lshlrev_b32_e32 v46, 16, v204
	v_and_b32_e32 v47, 0xffff0000, v204
	v_lshlrev_b32_e32 v48, 16, v205
	v_and_b32_e32 v49, 0xffff0000, v205
	v_lshlrev_b32_e32 v14, 16, v206
	v_and_b32_e32 v15, 0xffff0000, v206
	v_lshlrev_b32_e32 v16, 16, v207
	v_and_b32_e32 v17, 0xffff0000, v207
	v_lshlrev_b32_e32 v26, 16, v208
	v_and_b32_e32 v27, 0xffff0000, v208
	v_lshlrev_b32_e32 v28, 16, v209
	v_and_b32_e32 v29, 0xffff0000, v209
	v_lshlrev_b32_e32 v30, 16, v218
	v_and_b32_e32 v31, 0xffff0000, v218
	v_lshlrev_b32_e32 v32, 16, v219
	v_and_b32_e32 v33, 0xffff0000, v219
	v_lshlrev_b32_e32 v110, 16, v220
	v_and_b32_e32 v111, 0xffff0000, v220
	v_lshlrev_b32_e32 v112, 16, v221
	v_and_b32_e32 v113, 0xffff0000, v221
	v_lshlrev_b32_e32 v74, 16, v222
	v_and_b32_e32 v75, 0xffff0000, v222
	v_lshlrev_b32_e32 v76, 16, v223
	v_and_b32_e32 v77, 0xffff0000, v223
	v_lshlrev_b32_e32 v82, 16, v224
	v_and_b32_e32 v83, 0xffff0000, v224
	v_lshlrev_b32_e32 v84, 16, v225
	v_and_b32_e32 v85, 0xffff0000, v225
	v_lshlrev_b32_e32 v86, 16, v226
	v_and_b32_e32 v87, 0xffff0000, v226
	v_lshlrev_b32_e32 v88, 16, v227
	v_and_b32_e32 v89, 0xffff0000, v227
	v_lshlrev_b32_e32 v90, 16, v228
	v_and_b32_e32 v91, 0xffff0000, v228
	v_lshlrev_b32_e32 v92, 16, v229
	v_and_b32_e32 v93, 0xffff0000, v229
	v_lshlrev_b32_e32 v42, 16, v230
	v_and_b32_e32 v43, 0xffff0000, v230
	v_lshlrev_b32_e32 v44, 16, v231
	v_and_b32_e32 v45, 0xffff0000, v231
	v_lshlrev_b32_e32 v50, 16, v232
	v_and_b32_e32 v51, 0xffff0000, v232
	v_lshlrev_b32_e32 v52, 16, v233
	v_and_b32_e32 v53, 0xffff0000, v233
	v_lshlrev_b32_e32 v54, 16, v234
	v_and_b32_e32 v55, 0xffff0000, v234
	v_lshlrev_b32_e32 v56, 16, v235
	v_and_b32_e32 v57, 0xffff0000, v235
	v_lshlrev_b32_e32 v58, 16, v236
	v_and_b32_e32 v59, 0xffff0000, v236
	v_lshlrev_b32_e32 v60, 16, v237
	v_and_b32_e32 v61, 0xffff0000, v237
	v_lshlrev_b32_e32 v2, 16, v238
	v_and_b32_e32 v3, 0xffff0000, v238
	v_lshlrev_b32_e32 v4, 16, v239
	v_and_b32_e32 v5, 0xffff0000, v239
	v_lshlrev_b32_e32 v6, 16, v240
	v_and_b32_e32 v7, 0xffff0000, v240
	v_lshlrev_b32_e32 v8, 16, v241
	v_and_b32_e32 v9, 0xffff0000, v241
	v_lshlrev_b32_e32 v10, 16, v242
	v_and_b32_e32 v11, 0xffff0000, v242
	v_lshlrev_b32_e32 v12, 16, v243
	v_and_b32_e32 v13, 0xffff0000, v243
	v_lshlrev_b32_e32 v18, 16, v244
	v_and_b32_e32 v19, 0xffff0000, v244
	v_lshlrev_b32_e32 v20, 16, v245
	v_and_b32_e32 v21, 0xffff0000, v245
	s_mov_b64 s[18:19], 0

;     __device__ __forceinline__ void init(f32x4 (&acc)[2][2][4][2], const pg8::Unit& u, int wr, int wc, int fr, int fq) const {
;         const int col0 = u.pn * 256 + wc * 32 + 8 * fq;
;         const size_t off0 = (size_t)(u.pm * 256 + wr * 64 + fr) * D + col0;
; #pragma unroll
;         for (int ai = 0; ai < 2; ++ai)
; #pragma unroll
;             for (int m = 0; m < 4; ++m)
; #pragma unroll
;                 for (int bj = 0; bj < 2; ++bj) {
;                     const size_t off = off0 + (size_t)(ai * 128 + m * 16) * D + bj * 128;
;                     if (BASE_F32) { acc[ai][bj][m][0] = *(const f32x4*)(base32 + off); acc[ai][bj][m][1] = *(const f32x4*)(base32 + off + 4); }
;                     else { const u32x4 w = *(const u32x4*)(xb + off);
.LBB0_601:
	s_and_b64 vcc, exec, s[68:69]
	s_cbranch_vccnz .Lres_noinit
	v_lshl_add_u32 v172, s88, 8, v1
	v_ashrrev_i32_e32 v173, 31, v172
	v_lshl_or_b32 v246, s81, 8, v147
	v_lshlrev_b64 v[172:173], 11, v[172:173]
	v_ashrrev_i32_e32 v247, 31, v246
	v_lshl_add_u64 v[172:173], s[4:5], 0, v[172:173]
	v_lshl_add_u64 v[246:247], v[246:247], 1, v[172:173]
	s_mov_b32 s13, 0
	global_load_dwordx4 v[156:159], v[246:247], off
	global_load_dwordx4 v[160:163], v[246:247], off offset:256
	s_mov_b32 s12, 0x8000
	v_lshl_add_u64 v[172:173], v[246:247], 0, s[12:13]
	global_load_dwordx4 v[164:167], v[172:173], off
	global_load_dwordx4 v[168:171], v[172:173], off offset:256
	s_mov_b32 s12, 0x10000
	v_lshl_add_u64 v[172:173], v[246:247], 0, s[12:13]
	global_load_dwordx4 v[190:193], v[172:173], off
	global_load_dwordx4 v[194:197], v[172:173], off offset:256
	s_mov_b32 s12, 0x18000
	v_lshl_add_u64 v[172:173], v[246:247], 0, s[12:13]
	global_load_dwordx4 v[198:201], v[172:173], off
	global_load_dwordx4 v[202:205], v[172:173], off offset:256
	s_mov_b32 s12, 0x40000
	v_lshl_add_u64 v[172:173], v[246:247], 0, s[12:13]
	global_load_dwordx4 v[206:209], v[172:173], off
	global_load_dwordx4 v[218:221], v[172:173], off offset:256
	s_mov_b32 s12, 0x48000
	v_lshl_add_u64 v[172:173], v[246:247], 0, s[12:13]
	global_load_dwordx4 v[222:225], v[172:173], off
	global_load_dwordx4 v[226:229], v[172:173], off offset:256
	s_mov_b32 s12, 0x50000
	v_lshl_add_u64 v[172:173], v[246:247], 0, s[12:13]
	global_load_dwordx4 v[230:233], v[172:173], off
	global_load_dwordx4 v[234:237], v[172:173], off offset:256
	s_mov_b32 s12, 0x58000
	v_lshl_add_u64 v[172:173], v[246:247], 0, s[12:13]
	global_load_dwordx4 v[238:241], v[172:173], off
	global_load_dwordx4 v[242:245], v[172:173], off offset:256

; #define PG8_BAR __builtin_amdgcn_s_barrier()
;     __device__ __forceinline__ void init(f32x4 (&acc)[2][2][4][2], const pg8::Unit&, int, int, int, int) const { acc_zero(acc); }
;     __device__ __forceinline__ void init(f32x4 (&acc)[2][2][4][2], const pg8::Unit&, int, int, int, int) const { acc_zero(acc); }
;     __device__ __forceinline__ void init(f32x4 (&acc)[2][2][4][2], const pg8::Unit&, int, int, int, int) const { acc_zero(acc); }
;     __device__ __forceinline__ void init(f32x4 (&acc)[2][2][4][2], const pg8::Unit&, int, int, int, int) const { acc_zero(acc); }
; template <class Epi, class Sched>
; __device__ __forceinline__ void gemm_phase(LAS unsigned char* lds, const Gemm g, const Sched& S, const Epi& E) {
;     ...
;         if (!has_next) break;
;         E.init(acc, nxt, wr, wc, fr, fq);
;         cur = nxt; cA = nA; cB = nB; ++ui;
;         if (wr == 1) PG8_BAR;
.LBB0_617:
	s_or_b64 exec, exec, s[20:21]
	s_and_b64 vcc, exec, s[68:69]
	s_mov_b64 s[18:19], -1
	s_cbranch_vccnz .LBB0_586
	s_waitcnt lgkmcnt(0)
	s_andn2_b64 vcc, exec, s[82:83]
	s_cbranch_vccnz .LBB0_585
	s_barrier
	s_branch .LBB0_585
